# speedup vs baseline: 1.0182x; 1.0014x over previous
.LBB0_817:
	s_addk_i32 s6, 0x100
	v_add_u32_e32 v244, 0x400, v244
	s_cmpk_eq_i32 s6, 0x900
	v_add_u32_e32 v97, 0x400, v97
	s_cbranch_scc1 .LBB0_791
.LBB0_818:
	s_waitcnt lgkmcnt(9)
	v_pk_mul_f32 v[196:197], v[16:17], v[130:131]
	v_pk_mul_f32 v[198:199], v[18:19], v[132:133]
	v_pk_fma_f32 v[196:197], v[20:21], v[126:127], v[196:197]
	v_pk_fma_f32 v[198:199], v[22:23], v[128:129], v[198:199]
	v_pk_mul_f32 v[130:131], v[24:25], v[130:131]
	v_pk_add_f32 v[196:197], v[196:197], v[198:199]
	v_pk_fma_f32 v[126:127], v[28:29], v[126:127], v[130:131]
	v_add_f32_e32 v196, v196, v197
	v_pk_mul_f32 v[130:131], v[26:27], v[132:133]
	ds_read_b128 v[166:169], v97 offset:24576
	ds_read_b128 v[170:173], v97 offset:24592
	ds_read_b128 v[150:153], v97 offset:32768
	ds_read_b128 v[134:137], v97 offset:32784
	ds_read_b128 v[158:161], v97 offset:40960
	ds_read_b128 v[146:149], v97 offset:40976
	ds_read_b128 v[162:165], v97 offset:8192
	ds_read_b128 v[154:157], v97 offset:8208
	ds_read_b128 v[138:141], v97
	ds_read_b128 v[142:145], v97 offset:16
	ds_read_b64 v[194:195], v244
	v_add_f32_dpp v196, v196, v196 quad_perm:[1,0,3,2] row_mask:0xf bank_mask:0xf bound_ctrl:1
	v_pk_fma_f32 v[128:129], v[30:31], v[128:129], v[130:131]
	s_nop 0
	v_add_f32_dpp v196, v196, v196 quad_perm:[2,3,0,1] row_mask:0xf bank_mask:0xf bound_ctrl:1
	v_pk_add_f32 v[126:127], v[126:127], v[128:129]
	s_nop 0
	v_add_f32_dpp v196, v196, v196 row_half_mirror row_mask:0xf bank_mask:0xf bound_ctrl:1
	s_waitcnt lgkmcnt(14)
	v_pk_mul_f32 v[128:129], v[118:119], v[196:197] op_sel_hi:[1,0] neg_lo:[0,1] neg_hi:[0,1]
	v_add_f32_e32 v126, v126, v127
	s_waitcnt lgkmcnt(11)
	v_pk_fma_f32 v[128:129], v[122:123], v[192:193], v[128:129] op_sel_hi:[1,0,1]
	s_nop 0
	v_pk_fma_f32 v[128:129], v[20:21], v[98:99], v[128:129]
	v_pk_mul_f32 v[20:21], v[120:121], v[196:197] op_sel_hi:[1,0] neg_lo:[0,1] neg_hi:[0,1]
	v_add_f32_dpp v126, v126, v126 quad_perm:[1,0,3,2] row_mask:0xf bank_mask:0xf bound_ctrl:1
	v_pk_fma_f32 v[20:21], v[124:125], v[192:193], v[20:21] op_sel_hi:[1,0,1]
	s_nop 0
	v_pk_fma_f32 v[130:131], v[22:23], v[100:101], v[20:21]
	v_pk_mul_f32 v[20:21], v[102:103], v[196:197] op_sel_hi:[1,0] neg_lo:[0,1] neg_hi:[0,1]
	v_add_f32_dpp v126, v126, v126 quad_perm:[2,3,0,1] row_mask:0xf bank_mask:0xf bound_ctrl:1
	v_pk_fma_f32 v[20:21], v[110:111], v[192:193], v[20:21] op_sel_hi:[1,0,1]
	s_nop 0
	v_pk_fma_f32 v[132:133], v[16:17], v[92:93], v[20:21]
	v_pk_mul_f32 v[16:17], v[104:105], v[196:197] op_sel_hi:[1,0] neg_lo:[0,1] neg_hi:[0,1]
	v_add_f32_dpp v126, v126, v126 row_half_mirror row_mask:0xf bank_mask:0xf bound_ctrl:1
	v_pk_fma_f32 v[16:17], v[112:113], v[192:193], v[16:17] op_sel_hi:[1,0,1]
	s_nop 0
	v_pk_fma_f32 v[196:197], v[18:19], v[94:95], v[16:17]
	v_pk_mul_f32 v[16:17], v[114:115], v[132:133]
	v_pk_mul_f32 v[18:19], v[116:117], v[196:197]
	v_pk_fma_f32 v[16:17], v[106:107], v[128:129], v[16:17]
	v_pk_fma_f32 v[18:19], v[108:109], v[130:131], v[18:19]
	s_nop 0
	v_pk_add_f32 v[16:17], v[16:17], v[18:19]
	v_pk_mul_f32 v[18:19], v[118:119], v[126:127] op_sel_hi:[1,0] neg_lo:[0,1] neg_hi:[0,1]
	s_nop 0
	v_pk_fma_f32 v[18:19], v[122:123], v[192:193], v[18:19] op_sel:[0,1,0]
	s_nop 0
	v_pk_fma_f32 v[28:29], v[28:29], v[98:99], v[18:19]
	v_pk_mul_f32 v[18:19], v[120:121], v[126:127] op_sel_hi:[1,0] neg_lo:[0,1] neg_hi:[0,1]
	s_nop 0
	v_pk_fma_f32 v[18:19], v[124:125], v[192:193], v[18:19] op_sel:[0,1,0]
	s_nop 0
	v_pk_fma_f32 v[30:31], v[30:31], v[100:101], v[18:19]
	v_pk_mul_f32 v[18:19], v[102:103], v[126:127] op_sel_hi:[1,0] neg_lo:[0,1] neg_hi:[0,1]
	s_nop 0
	v_pk_fma_f32 v[18:19], v[110:111], v[192:193], v[18:19] op_sel:[0,1,0]
	s_nop 0
	v_pk_fma_f32 v[24:25], v[24:25], v[92:93], v[18:19]
	v_pk_mul_f32 v[18:19], v[104:105], v[126:127] op_sel_hi:[1,0] neg_lo:[0,1] neg_hi:[0,1]
	s_nop 0
	v_pk_fma_f32 v[18:19], v[112:113], v[192:193], v[18:19] op_sel:[0,1,0]
	s_nop 0
	v_pk_fma_f32 v[26:27], v[26:27], v[94:95], v[18:19]
	v_pk_mul_f32 v[18:19], v[114:115], v[24:25]
	v_pk_mul_f32 v[20:21], v[116:117], v[26:27]
	v_pk_fma_f32 v[18:19], v[106:107], v[28:29], v[18:19]
	v_pk_fma_f32 v[20:21], v[108:109], v[30:31], v[20:21]
	s_nop 0
	v_pk_add_f32 v[18:19], v[18:19], v[20:21]
	s_nop 0
	v_add_f32_e32 v16, v16, v17
	v_add_f32_e32 v17, v18, v19
	s_nop 0
	v_add_f32_dpp v16, v16, v16 quad_perm:[1,0,3,2] row_mask:0xf bank_mask:0xf bound_ctrl:1
	v_add_f32_dpp v17, v17, v17 quad_perm:[1,0,3,2] row_mask:0xf bank_mask:0xf bound_ctrl:1
	s_nop 0
	v_add_f32_dpp v16, v16, v16 quad_perm:[2,3,0,1] row_mask:0xf bank_mask:0xf bound_ctrl:1
	v_add_f32_dpp v17, v17, v17 quad_perm:[2,3,0,1] row_mask:0xf bank_mask:0xf bound_ctrl:1
	s_nop 0
	v_add_f32_dpp v16, v16, v16 row_half_mirror row_mask:0xf bank_mask:0xf bound_ctrl:1
	v_add_f32_dpp v17, v17, v17 row_half_mirror row_mask:0xf bank_mask:0xf bound_ctrl:1
	ds_write_b64 v244, v[16:17] offset:42240
	s_waitcnt lgkmcnt(9)
	v_pk_mul_f32 v[192:193], v[132:133], v[170:171]
	v_pk_mul_f32 v[198:199], v[196:197], v[172:173]
	v_pk_fma_f32 v[192:193], v[128:129], v[166:167], v[192:193]
	v_pk_fma_f32 v[198:199], v[130:131], v[168:169], v[198:199]
	v_pk_mul_f32 v[170:171], v[24:25], v[170:171]
	v_pk_add_f32 v[192:193], v[192:193], v[198:199]
	v_pk_fma_f32 v[166:167], v[28:29], v[166:167], v[170:171]
	v_add_f32_e32 v192, v192, v193
	v_pk_mul_f32 v[170:171], v[26:27], v[172:173]
	ds_read_b128 v[118:121], v97 offset:24832
	ds_read_b128 v[122:125], v97 offset:24848
	ds_read_b128 v[102:105], v97 offset:33024
	ds_read_b128 v[16:19], v97 offset:33040
	ds_read_b128 v[110:113], v97 offset:41216
	ds_read_b128 v[98:101], v97 offset:41232
	ds_read_b128 v[114:117], v97 offset:8448
	ds_read_b128 v[106:109], v97 offset:8464
	ds_read_b128 v[20:23], v97 offset:256
	ds_read_b128 v[92:95], v97 offset:272
	ds_read_b64 v[126:127], v244 offset:256
	v_add_f32_dpp v192, v192, v192 quad_perm:[1,0,3,2] row_mask:0xf bank_mask:0xf bound_ctrl:1
	v_pk_fma_f32 v[168:169], v[30:31], v[168:169], v[170:171]
	s_nop 0
	v_add_f32_dpp v192, v192, v192 quad_perm:[2,3,0,1] row_mask:0xf bank_mask:0xf bound_ctrl:1
	v_pk_add_f32 v[166:167], v[166:167], v[168:169]
	s_nop 0
	v_add_f32_dpp v192, v192, v192 row_half_mirror row_mask:0xf bank_mask:0xf bound_ctrl:1
	s_waitcnt lgkmcnt(14)
	v_pk_mul_f32 v[168:169], v[158:159], v[192:193] op_sel_hi:[1,0] neg_lo:[0,1] neg_hi:[0,1]
	v_add_f32_e32 v166, v166, v167
	s_waitcnt lgkmcnt(11)
	v_pk_fma_f32 v[168:169], v[162:163], v[194:195], v[168:169] op_sel_hi:[1,0,1]
	s_nop 0
	v_pk_fma_f32 v[128:129], v[128:129], v[150:151], v[168:169]
	v_pk_mul_f32 v[168:169], v[160:161], v[192:193] op_sel_hi:[1,0] neg_lo:[0,1] neg_hi:[0,1]
	v_add_f32_dpp v166, v166, v166 quad_perm:[1,0,3,2] row_mask:0xf bank_mask:0xf bound_ctrl:1
	v_pk_fma_f32 v[168:169], v[164:165], v[194:195], v[168:169] op_sel_hi:[1,0,1]
	s_nop 0
	v_add_f32_dpp v166, v166, v166 quad_perm:[2,3,0,1] row_mask:0xf bank_mask:0xf bound_ctrl:1
	v_pk_fma_f32 v[130:131], v[130:131], v[152:153], v[168:169]
	v_pk_mul_f32 v[168:169], v[146:147], v[192:193] op_sel_hi:[1,0] neg_lo:[0,1] neg_hi:[0,1]
	v_add_f32_dpp v166, v166, v166 row_half_mirror row_mask:0xf bank_mask:0xf bound_ctrl:1
	v_pk_fma_f32 v[168:169], v[154:155], v[194:195], v[168:169] op_sel_hi:[1,0,1]
	v_pk_mul_f32 v[158:159], v[158:159], v[166:167] op_sel_hi:[1,0] neg_lo:[0,1] neg_hi:[0,1]
	v_pk_fma_f32 v[132:133], v[132:133], v[134:135], v[168:169]
	v_pk_mul_f32 v[168:169], v[148:149], v[192:193] op_sel_hi:[1,0] neg_lo:[0,1] neg_hi:[0,1]
	v_pk_fma_f32 v[158:159], v[162:163], v[194:195], v[158:159] op_sel:[0,1,0]
	v_pk_fma_f32 v[168:169], v[156:157], v[194:195], v[168:169] op_sel_hi:[1,0,1]
	s_nop 0
	v_pk_fma_f32 v[192:193], v[196:197], v[136:137], v[168:169]
	v_pk_fma_f32 v[196:197], v[28:29], v[150:151], v[158:159]
	v_pk_mul_f32 v[28:29], v[160:161], v[166:167] op_sel_hi:[1,0] neg_lo:[0,1] neg_hi:[0,1]
	v_pk_mul_f32 v[168:169], v[142:143], v[132:133]
	v_pk_fma_f32 v[28:29], v[164:165], v[194:195], v[28:29] op_sel:[0,1,0]
	v_pk_mul_f32 v[170:171], v[144:145], v[192:193]
	v_pk_fma_f32 v[198:199], v[30:31], v[152:153], v[28:29]
	v_pk_mul_f32 v[28:29], v[146:147], v[166:167] op_sel_hi:[1,0] neg_lo:[0,1] neg_hi:[0,1]
	v_pk_fma_f32 v[168:169], v[138:139], v[128:129], v[168:169]
	v_pk_fma_f32 v[28:29], v[154:155], v[194:195], v[28:29] op_sel:[0,1,0]
	v_pk_fma_f32 v[170:171], v[140:141], v[130:131], v[170:171]
	v_pk_fma_f32 v[200:201], v[24:25], v[134:135], v[28:29]
	v_pk_mul_f32 v[24:25], v[148:149], v[166:167] op_sel_hi:[1,0] neg_lo:[0,1] neg_hi:[0,1]
	v_pk_add_f32 v[168:169], v[168:169], v[170:171]
	v_pk_fma_f32 v[24:25], v[156:157], v[194:195], v[24:25] op_sel:[0,1,0]
	s_nop 0
	v_pk_fma_f32 v[202:203], v[26:27], v[136:137], v[24:25]
	v_pk_mul_f32 v[24:25], v[142:143], v[200:201]
	v_pk_mul_f32 v[26:27], v[144:145], v[202:203]
	v_pk_fma_f32 v[24:25], v[138:139], v[196:197], v[24:25]
	v_pk_fma_f32 v[26:27], v[140:141], v[198:199], v[26:27]
	s_nop 0
	v_pk_add_f32 v[24:25], v[24:25], v[26:27]
	s_nop 0
	v_add_f32_e32 v25, v24, v25
	v_add_f32_e32 v24, v168, v169
	s_nop 0
	v_add_f32_dpp v25, v25, v25 quad_perm:[1,0,3,2] row_mask:0xf bank_mask:0xf bound_ctrl:1
	v_add_f32_dpp v24, v24, v24 quad_perm:[1,0,3,2] row_mask:0xf bank_mask:0xf bound_ctrl:1
	s_nop 0
	v_add_f32_dpp v25, v25, v25 quad_perm:[2,3,0,1] row_mask:0xf bank_mask:0xf bound_ctrl:1
	v_add_f32_dpp v24, v24, v24 quad_perm:[2,3,0,1] row_mask:0xf bank_mask:0xf bound_ctrl:1
	s_nop 0
	v_add_f32_dpp v25, v25, v25 row_half_mirror row_mask:0xf bank_mask:0xf bound_ctrl:1
	v_add_f32_dpp v24, v24, v24 row_half_mirror row_mask:0xf bank_mask:0xf bound_ctrl:1
	ds_write_b64 v244, v[24:25] offset:42496
	s_waitcnt lgkmcnt(9)
	v_pk_mul_f32 v[168:169], v[132:133], v[122:123]
	v_pk_mul_f32 v[170:171], v[192:193], v[124:125]
	v_pk_fma_f32 v[168:169], v[128:129], v[118:119], v[168:169]
	v_pk_fma_f32 v[170:171], v[130:131], v[120:121], v[170:171]
	v_pk_mul_f32 v[122:123], v[200:201], v[122:123]
	v_pk_add_f32 v[168:169], v[168:169], v[170:171]
	v_pk_fma_f32 v[118:119], v[196:197], v[118:119], v[122:123]
	v_add_f32_e32 v168, v168, v169
	v_pk_mul_f32 v[122:123], v[202:203], v[124:125]
	ds_read_b128 v[158:161], v97 offset:25088
	ds_read_b128 v[162:165], v97 offset:25104
	ds_read_b128 v[28:31], v97 offset:33280
	ds_read_b128 v[24:27], v97 offset:33296
	ds_read_b128 v[150:153], v97 offset:41472
	ds_read_b128 v[142:145], v97 offset:41488
	ds_read_b128 v[154:157], v97 offset:8704
	ds_read_b128 v[146:149], v97 offset:8720
	ds_read_b128 v[134:137], v97 offset:512
	ds_read_b128 v[138:141], v97 offset:528
	ds_read_b64 v[166:167], v244 offset:512
	v_add_f32_dpp v168, v168, v168 quad_perm:[1,0,3,2] row_mask:0xf bank_mask:0xf bound_ctrl:1
	v_pk_fma_f32 v[120:121], v[198:199], v[120:121], v[122:123]
	s_nop 0
	v_add_f32_dpp v168, v168, v168 quad_perm:[2,3,0,1] row_mask:0xf bank_mask:0xf bound_ctrl:1
	v_pk_add_f32 v[118:119], v[118:119], v[120:121]
	s_nop 0
	v_add_f32_dpp v194, v168, v168 row_half_mirror row_mask:0xf bank_mask:0xf bound_ctrl:1
	v_add_f32_e32 v118, v118, v119
	s_waitcnt lgkmcnt(14)
	v_pk_mul_f32 v[120:121], v[110:111], v[194:195] op_sel_hi:[1,0] neg_lo:[0,1] neg_hi:[0,1]
	v_add_f32_dpp v118, v118, v118 quad_perm:[1,0,3,2] row_mask:0xf bank_mask:0xf bound_ctrl:1
	s_waitcnt lgkmcnt(11)
	v_pk_fma_f32 v[120:121], v[114:115], v[126:127], v[120:121] op_sel_hi:[1,0,1]
	v_add_f32_dpp v118, v118, v118 quad_perm:[2,3,0,1] row_mask:0xf bank_mask:0xf bound_ctrl:1
	v_pk_fma_f32 v[168:169], v[128:129], v[102:103], v[120:121]
	v_pk_mul_f32 v[120:121], v[112:113], v[194:195] op_sel_hi:[1,0] neg_lo:[0,1] neg_hi:[0,1]
	v_add_f32_dpp v118, v118, v118 row_half_mirror row_mask:0xf bank_mask:0xf bound_ctrl:1
	v_pk_fma_f32 v[120:121], v[116:117], v[126:127], v[120:121] op_sel_hi:[1,0,1]
	v_pk_mul_f32 v[110:111], v[110:111], v[118:119] op_sel_hi:[1,0] neg_lo:[0,1] neg_hi:[0,1]
	v_pk_fma_f32 v[170:171], v[130:131], v[104:105], v[120:121]
	v_pk_mul_f32 v[120:121], v[98:99], v[194:195] op_sel_hi:[1,0] neg_lo:[0,1] neg_hi:[0,1]
	v_pk_mul_f32 v[98:99], v[98:99], v[118:119] op_sel_hi:[1,0] neg_lo:[0,1] neg_hi:[0,1]
	v_pk_fma_f32 v[120:121], v[106:107], v[126:127], v[120:121] op_sel_hi:[1,0,1]
	v_pk_fma_f32 v[98:99], v[106:107], v[126:127], v[98:99] op_sel:[0,1,0]
	v_pk_fma_f32 v[172:173], v[132:133], v[16:17], v[120:121]
	v_pk_mul_f32 v[120:121], v[100:101], v[194:195] op_sel_hi:[1,0] neg_lo:[0,1] neg_hi:[0,1]
	v_pk_fma_f32 v[110:111], v[114:115], v[126:127], v[110:111] op_sel:[0,1,0]
	v_pk_fma_f32 v[200:201], v[200:201], v[16:17], v[98:99]
	v_pk_mul_f32 v[16:17], v[100:101], v[118:119] op_sel_hi:[1,0] neg_lo:[0,1] neg_hi:[0,1]
	v_pk_fma_f32 v[120:121], v[108:109], v[126:127], v[120:121] op_sel_hi:[1,0,1]
	v_pk_fma_f32 v[196:197], v[196:197], v[102:103], v[110:111]
	v_pk_mul_f32 v[102:103], v[112:113], v[118:119] op_sel_hi:[1,0] neg_lo:[0,1] neg_hi:[0,1]
	v_pk_fma_f32 v[16:17], v[108:109], v[126:127], v[16:17] op_sel:[0,1,0]
	v_pk_fma_f32 v[194:195], v[192:193], v[18:19], v[120:121]
	v_pk_fma_f32 v[102:103], v[116:117], v[126:127], v[102:103] op_sel:[0,1,0]
	v_pk_fma_f32 v[202:203], v[202:203], v[18:19], v[16:17]
	v_pk_mul_f32 v[120:121], v[92:93], v[172:173]
	v_pk_mul_f32 v[122:123], v[94:95], v[194:195]
	v_pk_fma_f32 v[198:199], v[198:199], v[104:105], v[102:103]
	v_pk_mul_f32 v[16:17], v[92:93], v[200:201]
	v_pk_mul_f32 v[18:19], v[94:95], v[202:203]
	v_pk_fma_f32 v[120:121], v[20:21], v[168:169], v[120:121]
	v_pk_fma_f32 v[122:123], v[22:23], v[170:171], v[122:123]
	v_pk_fma_f32 v[16:17], v[20:21], v[196:197], v[16:17]
	v_pk_fma_f32 v[18:19], v[22:23], v[198:199], v[18:19]
	v_pk_add_f32 v[120:121], v[120:121], v[122:123]
	v_pk_add_f32 v[16:17], v[16:17], v[18:19]
	s_nop 0
	v_add_f32_e32 v17, v16, v17
	v_add_f32_e32 v16, v120, v121
	s_nop 0
	v_add_f32_dpp v17, v17, v17 quad_perm:[1,0,3,2] row_mask:0xf bank_mask:0xf bound_ctrl:1
	v_add_f32_dpp v16, v16, v16 quad_perm:[1,0,3,2] row_mask:0xf bank_mask:0xf bound_ctrl:1
	s_nop 0
	v_add_f32_dpp v17, v17, v17 quad_perm:[2,3,0,1] row_mask:0xf bank_mask:0xf bound_ctrl:1
	v_add_f32_dpp v16, v16, v16 quad_perm:[2,3,0,1] row_mask:0xf bank_mask:0xf bound_ctrl:1
	s_nop 0
	v_add_f32_dpp v17, v17, v17 row_half_mirror row_mask:0xf bank_mask:0xf bound_ctrl:1
	v_add_f32_dpp v16, v16, v16 row_half_mirror row_mask:0xf bank_mask:0xf bound_ctrl:1
	ds_write_b64 v244, v[16:17] offset:42752
	s_and_b32 s0, s6, 0x700
	v_or_b32_e32 v16, s0, v174
	v_lshlrev_b32_e32 v16, 2, v16
	ds_read_b128 v[126:129], v16 offset:24576
	ds_read_b128 v[130:133], v16 offset:24592
	ds_read_b128 v[98:101], v16 offset:32768
	ds_read_b128 v[92:95], v16 offset:32784
	ds_read_b128 v[118:121], v16 offset:40960
	ds_read_b128 v[102:105], v16 offset:40976
	ds_read_b128 v[122:125], v16 offset:8192
	ds_read_b128 v[110:113], v16 offset:8208
	ds_read_b128 v[106:109], v16
	ds_read_b128 v[114:117], v16 offset:16
	v_lshl_add_u32 v16, s0, 2, v236
	ds_read_b64 v[192:193], v16 offset:16384
	s_waitcnt lgkmcnt(14)
	v_pk_mul_f32 v[16:17], v[172:173], v[162:163]
	v_pk_mul_f32 v[18:19], v[194:195], v[164:165]
	v_pk_fma_f32 v[16:17], v[168:169], v[158:159], v[16:17]
	v_pk_fma_f32 v[18:19], v[170:171], v[160:161], v[18:19]
	v_pk_mul_f32 v[20:21], v[202:203], v[164:165]
	v_pk_add_f32 v[16:17], v[16:17], v[18:19]
	v_pk_fma_f32 v[20:21], v[198:199], v[160:161], v[20:21]
	v_add_f32_e32 v16, v16, v17
	s_nop 1
	v_add_f32_dpp v16, v16, v16 quad_perm:[1,0,3,2] row_mask:0xf bank_mask:0xf bound_ctrl:1
	s_nop 1
	v_add_f32_dpp v16, v16, v16 quad_perm:[2,3,0,1] row_mask:0xf bank_mask:0xf bound_ctrl:1
	s_nop 1
	v_add_f32_dpp v18, v16, v16 row_half_mirror row_mask:0xf bank_mask:0xf bound_ctrl:1
	v_pk_mul_f32 v[16:17], v[200:201], v[162:163]
	s_nop 0
	v_pk_fma_f32 v[16:17], v[196:197], v[158:159], v[16:17]
	s_nop 0
	v_pk_add_f32 v[16:17], v[16:17], v[20:21]
	s_nop 0
	v_add_f32_e32 v16, v16, v17
	s_nop 1
	v_add_f32_dpp v16, v16, v16 quad_perm:[1,0,3,2] row_mask:0xf bank_mask:0xf bound_ctrl:1
	s_nop 1
	v_add_f32_dpp v16, v16, v16 quad_perm:[2,3,0,1] row_mask:0xf bank_mask:0xf bound_ctrl:1
	s_nop 1
	v_add_f32_dpp v158, v16, v16 row_half_mirror row_mask:0xf bank_mask:0xf bound_ctrl:1
	v_pk_mul_f32 v[16:17], v[150:151], v[18:19] op_sel_hi:[1,0] neg_lo:[0,1] neg_hi:[0,1]
	v_pk_mul_f32 v[150:151], v[150:151], v[158:159] op_sel_hi:[1,0] neg_lo:[0,1] neg_hi:[0,1]
	s_waitcnt lgkmcnt(11)
	v_pk_fma_f32 v[16:17], v[154:155], v[166:167], v[16:17] op_sel_hi:[1,0,1]
	v_pk_fma_f32 v[150:151], v[154:155], v[166:167], v[150:151] op_sel:[0,1,0]
	v_pk_fma_f32 v[20:21], v[168:169], v[28:29], v[16:17]
	v_pk_mul_f32 v[16:17], v[152:153], v[18:19] op_sel_hi:[1,0] neg_lo:[0,1] neg_hi:[0,1]
	v_pk_fma_f32 v[28:29], v[196:197], v[28:29], v[150:151]
	v_pk_fma_f32 v[16:17], v[156:157], v[166:167], v[16:17] op_sel_hi:[1,0,1]
	v_pk_mul_f32 v[150:151], v[152:153], v[158:159] op_sel_hi:[1,0] neg_lo:[0,1] neg_hi:[0,1]
	v_pk_fma_f32 v[22:23], v[170:171], v[30:31], v[16:17]
	v_pk_mul_f32 v[16:17], v[142:143], v[18:19] op_sel_hi:[1,0] neg_lo:[0,1] neg_hi:[0,1]
	v_pk_mul_f32 v[142:143], v[142:143], v[158:159] op_sel_hi:[1,0] neg_lo:[0,1] neg_hi:[0,1]
	v_pk_fma_f32 v[16:17], v[146:147], v[166:167], v[16:17] op_sel_hi:[1,0,1]
	v_pk_fma_f32 v[142:143], v[146:147], v[166:167], v[142:143] op_sel:[0,1,0]
	v_pk_fma_f32 v[16:17], v[172:173], v[24:25], v[16:17]
	v_pk_mul_f32 v[18:19], v[144:145], v[18:19] op_sel_hi:[1,0] neg_lo:[0,1] neg_hi:[0,1]
	v_pk_fma_f32 v[24:25], v[200:201], v[24:25], v[142:143]
	v_pk_mul_f32 v[142:143], v[144:145], v[158:159] op_sel_hi:[1,0] neg_lo:[0,1] neg_hi:[0,1]
	v_pk_fma_f32 v[18:19], v[148:149], v[166:167], v[18:19] op_sel_hi:[1,0,1]
	v_pk_fma_f32 v[142:143], v[148:149], v[166:167], v[142:143] op_sel:[0,1,0]
	v_pk_fma_f32 v[18:19], v[194:195], v[26:27], v[18:19]
	v_pk_mul_f32 v[160:161], v[138:139], v[16:17]
	v_pk_fma_f32 v[150:151], v[156:157], v[166:167], v[150:151] op_sel:[0,1,0]
	v_pk_fma_f32 v[26:27], v[202:203], v[26:27], v[142:143]
	v_pk_mul_f32 v[138:139], v[138:139], v[24:25]
	v_pk_fma_f32 v[160:161], v[134:135], v[20:21], v[160:161]
	v_pk_mul_f32 v[162:163], v[140:141], v[18:19]
	v_pk_fma_f32 v[30:31], v[198:199], v[30:31], v[150:151]
	v_pk_fma_f32 v[134:135], v[134:135], v[28:29], v[138:139]
	v_pk_mul_f32 v[138:139], v[140:141], v[26:27]
	v_pk_fma_f32 v[162:163], v[136:137], v[22:23], v[162:163]
	v_pk_fma_f32 v[136:137], v[136:137], v[30:31], v[138:139]
	v_pk_add_f32 v[160:161], v[160:161], v[162:163]
	v_pk_add_f32 v[134:135], v[134:135], v[136:137]
	s_nop 0
	v_add_f32_e32 v135, v134, v135
	v_add_f32_e32 v134, v160, v161
	s_nop 0
	v_add_f32_dpp v135, v135, v135 quad_perm:[1,0,3,2] row_mask:0xf bank_mask:0xf bound_ctrl:1
	v_add_f32_dpp v134, v134, v134 quad_perm:[1,0,3,2] row_mask:0xf bank_mask:0xf bound_ctrl:1
	s_nop 0
	v_add_f32_dpp v135, v135, v135 quad_perm:[2,3,0,1] row_mask:0xf bank_mask:0xf bound_ctrl:1
	v_add_f32_dpp v134, v134, v134 quad_perm:[2,3,0,1] row_mask:0xf bank_mask:0xf bound_ctrl:1
	s_nop 0
	v_add_f32_dpp v135, v135, v135 row_half_mirror row_mask:0xf bank_mask:0xf bound_ctrl:1
	v_add_f32_dpp v134, v134, v134 row_half_mirror row_mask:0xf bank_mask:0xf bound_ctrl:1
	ds_write_b64 v244, v[134:135] offset:43008
	s_branch .LBB0_817
